# in-proj epilogue PROJ stores as buffer_store_dwordx4 (SRD base + 32-bit VGPR offset, soffset for the second head slab) instead of 64-bit VGPR global stores
# speedup vs baseline: 1.0003x; 1.0003x over previous
.LBB0_132:
	v_lshl_add_u32 v142, s26, 8, v162
	s_lshl_b32 s26, s43, 1
	s_ashr_i32 s27, s26, 31
	s_lshl_b64 s[2:3], s[26:27], 21
	v_ashrrev_i32_e32 v143, 31, v142
	v_lshl_add_u64 v[144:145], v[136:137], 0, s[2:3]
	s_nop 1
	v_readfirstlane_b32 s84, v144
	v_readfirstlane_b32 s85, v145
	s_nop 1
	v_subrev_u32_e32 v174, s84, v144
	s_and_b32 s85, s85, 0xffff
	s_mov_b32 s86, -1
	s_mov_b32 s87, 0x20000
	s_mov_b32 s88, 0x200000
	v_lshl_add_u32 v175, v142, 8, v174
	v_cvt_pk_bf16_f32 v150, v126, v127
	v_cvt_pk_bf16_f32 v151, v128, v129
	v_cvt_pk_bf16_f32 v152, v122, v123
	v_cvt_pk_bf16_f32 v153, v124, v125
	buffer_store_dwordx4 v[150:153], v175, s[84:87], 0 offen
	v_mov_b32_e32 v147, v146
	v_pk_mul_f32 v[118:119], v[118:119], v[146:147]
	v_mov_b32_e32 v150, v146
	v_mov_b32_e32 v151, v146
	v_pk_mul_f32 v[120:121], v[120:121], v[150:151]
	v_pk_mul_f32 v[116:117], v[116:117], v[150:151]
	v_cndmask_b32_e64 v150, 0, 1, s[0:1]
	v_cmp_ne_u32_e64 s[4:5], 1, v150
	s_andn2_b64 vcc, exec, s[0:1]
	v_pk_mul_f32 v[114:115], v[114:115], v[146:147]
	s_cbranch_vccnz .LBB0_134
	v_mul_f32_e32 v146, 0xbfb8aa3b, v118
	v_mul_f32_e32 v147, 0xbfb8aa3b, v119
	v_mul_f32_e32 v150, 0xbfb8aa3b, v120
	v_mul_f32_e32 v151, 0xbfb8aa3b, v121
	v_exp_f32_e32 v146, v146
	v_exp_f32_e32 v147, v147
	v_exp_f32_e32 v150, v150
	v_exp_f32_e32 v151, v151
	v_add_f32_e32 v146, 1.0, v146
	v_add_f32_e32 v147, 1.0, v147
	v_add_f32_e32 v150, 1.0, v150
	v_add_f32_e32 v151, 1.0, v151
	v_rcp_f32_e32 v146, v146
	v_rcp_f32_e32 v147, v147
	v_rcp_f32_e32 v150, v150
	v_rcp_f32_e32 v151, v151
	v_pk_mul_f32 v[118:119], v[118:119], v[146:147]
	v_mul_f32_e32 v146, 0xbfb8aa3b, v114
	v_pk_mul_f32 v[120:121], v[120:121], v[150:151]
	v_mul_f32_e32 v147, 0xbfb8aa3b, v115
	v_mul_f32_e32 v150, 0xbfb8aa3b, v116
	v_mul_f32_e32 v151, 0xbfb8aa3b, v117
	v_exp_f32_e32 v146, v146
	v_exp_f32_e32 v147, v147
	v_exp_f32_e32 v150, v150
	v_exp_f32_e32 v151, v151
	v_add_f32_e32 v146, 1.0, v146
	v_add_f32_e32 v147, 1.0, v147
	v_add_f32_e32 v150, 1.0, v150
	v_add_f32_e32 v151, 1.0, v151
	v_rcp_f32_e32 v146, v146
	v_rcp_f32_e32 v147, v147
	v_rcp_f32_e32 v150, v150
	v_rcp_f32_e32 v151, v151
	v_pk_mul_f32 v[114:115], v[114:115], v[146:147]
	v_pk_mul_f32 v[116:117], v[116:117], v[150:151]
.LBB0_134:
	v_cvt_pk_bf16_f32 v150, v118, v119
	v_cvt_pk_bf16_f32 v151, v120, v121
	v_cvt_pk_bf16_f32 v152, v114, v115
	s_nop 0
	v_cvt_pk_bf16_f32 v153, v116, v117
	ds_read_b32 v148, v168 offset:64
	s_nop 0
	s_and_b64 vcc, exec, s[4:5]
	buffer_store_dwordx4 v[150:153], v175, s[84:87], s88 offen
	s_waitcnt lgkmcnt(0)
	v_pk_mul_f32 v[112:113], v[112:113], v[148:149] op_sel_hi:[1,0]
	v_pk_mul_f32 v[110:111], v[110:111], v[148:149] op_sel_hi:[1,0]
	v_pk_mul_f32 v[108:109], v[108:109], v[148:149] op_sel_hi:[1,0]
	v_pk_mul_f32 v[106:107], v[106:107], v[148:149] op_sel_hi:[1,0]
	s_cbranch_vccnz .LBB0_136
	v_mul_f32_e32 v149, 0xbfb8aa3b, v112
	v_exp_f32_e32 v149, v149
	v_mul_f32_e32 v146, 0xbfb8aa3b, v110
	v_mul_f32_e32 v147, 0xbfb8aa3b, v111
	v_exp_f32_e32 v146, v146
	v_add_f32_e32 v149, 1.0, v149
	v_rcp_f32_e32 v150, v149
	v_mul_f32_e32 v149, 0xbfb8aa3b, v113
	v_exp_f32_e32 v149, v149
	v_exp_f32_e32 v147, v147
	v_add_f32_e32 v146, 1.0, v146
	v_rcp_f32_e32 v146, v146
	v_add_f32_e32 v149, 1.0, v149
	v_rcp_f32_e32 v151, v149
	v_mul_f32_e32 v149, 0xbfb8aa3b, v108
	v_add_f32_e32 v147, 1.0, v147
	v_exp_f32_e32 v149, v149
	v_rcp_f32_e32 v147, v147
	v_pk_mul_f32 v[112:113], v[112:113], v[150:151]
	v_add_f32_e32 v149, 1.0, v149
	v_pk_mul_f32 v[110:111], v[110:111], v[146:147]
	v_mul_f32_e32 v146, 0xbfb8aa3b, v106
	v_mul_f32_e32 v147, 0xbfb8aa3b, v107
	v_rcp_f32_e32 v150, v149
	v_mul_f32_e32 v149, 0xbfb8aa3b, v109
	v_exp_f32_e32 v146, v146
	v_exp_f32_e32 v147, v147
	v_exp_f32_e32 v149, v149
	v_add_f32_e32 v146, 1.0, v146
	v_add_f32_e32 v147, 1.0, v147
	v_add_f32_e32 v149, 1.0, v149
	v_rcp_f32_e32 v146, v146
	v_rcp_f32_e32 v147, v147
	v_rcp_f32_e32 v151, v149
	v_pk_mul_f32 v[106:107], v[106:107], v[146:147]
	v_pk_mul_f32 v[108:109], v[108:109], v[150:151]
.LBB0_136:
	v_or_b32_e32 v146, 16, v142
	v_ashrrev_i32_e32 v147, 31, v146
	v_lshl_add_u32 v175, v146, 8, v174
	v_cvt_pk_bf16_f32 v152, v110, v111
	v_cvt_pk_bf16_f32 v153, v112, v113
	v_mov_b32_e32 v149, v148
	v_cvt_pk_bf16_f32 v154, v106, v107
	v_cvt_pk_bf16_f32 v155, v108, v109
	buffer_store_dwordx4 v[152:155], v175, s[84:87], 0 offen
	v_pk_mul_f32 v[102:103], v[102:103], v[148:149]
	s_and_b64 vcc, exec, s[4:5]
	v_mov_b32_e32 v152, v148
	v_mov_b32_e32 v153, v148
	v_pk_mul_f32 v[104:105], v[104:105], v[152:153]
	v_pk_mul_f32 v[100:101], v[100:101], v[152:153]
	v_pk_mul_f32 v[98:99], v[98:99], v[148:149]
	s_cbranch_vccnz .LBB0_138
	v_mul_f32_e32 v148, 0xbfb8aa3b, v102
	v_mul_f32_e32 v149, 0xbfb8aa3b, v103
	v_mul_f32_e32 v152, 0xbfb8aa3b, v104
	v_mul_f32_e32 v153, 0xbfb8aa3b, v105
	v_exp_f32_e32 v148, v148
	v_exp_f32_e32 v149, v149
	v_exp_f32_e32 v152, v152
	v_exp_f32_e32 v153, v153
	v_add_f32_e32 v148, 1.0, v148
	v_add_f32_e32 v149, 1.0, v149
	v_add_f32_e32 v152, 1.0, v152
	v_add_f32_e32 v153, 1.0, v153
	v_rcp_f32_e32 v148, v148
	v_rcp_f32_e32 v149, v149
	v_rcp_f32_e32 v152, v152
	v_rcp_f32_e32 v153, v153
	v_pk_mul_f32 v[102:103], v[102:103], v[148:149]
	v_mul_f32_e32 v148, 0xbfb8aa3b, v98
	v_pk_mul_f32 v[104:105], v[104:105], v[152:153]
	v_mul_f32_e32 v149, 0xbfb8aa3b, v99
	v_mul_f32_e32 v152, 0xbfb8aa3b, v100
	v_mul_f32_e32 v153, 0xbfb8aa3b, v101
	v_exp_f32_e32 v148, v148
	v_exp_f32_e32 v149, v149
	v_exp_f32_e32 v152, v152
	v_exp_f32_e32 v153, v153
	v_add_f32_e32 v148, 1.0, v148
	v_add_f32_e32 v149, 1.0, v149
	v_add_f32_e32 v152, 1.0, v152
	v_add_f32_e32 v153, 1.0, v153
	v_rcp_f32_e32 v148, v148
	v_rcp_f32_e32 v149, v149
	v_rcp_f32_e32 v152, v152
	v_rcp_f32_e32 v153, v153
	v_pk_mul_f32 v[98:99], v[98:99], v[148:149]
	v_pk_mul_f32 v[100:101], v[100:101], v[152:153]
.LBB0_138:
	v_cvt_pk_bf16_f32 v152, v102, v103
	v_cvt_pk_bf16_f32 v153, v104, v105
	v_cvt_pk_bf16_f32 v154, v98, v99
	s_nop 0
	v_cvt_pk_bf16_f32 v155, v100, v101
	ds_read_b32 v150, v168 offset:128
	s_nop 0
	s_and_b64 vcc, exec, s[4:5]
	buffer_store_dwordx4 v[152:155], v175, s[84:87], s88 offen
	s_waitcnt lgkmcnt(0)
	v_pk_mul_f32 v[96:97], v[96:97], v[150:151] op_sel_hi:[1,0]
	v_pk_mul_f32 v[94:95], v[94:95], v[150:151] op_sel_hi:[1,0]
	v_pk_mul_f32 v[92:93], v[92:93], v[150:151] op_sel_hi:[1,0]
	v_pk_mul_f32 v[90:91], v[90:91], v[150:151] op_sel_hi:[1,0]
	s_cbranch_vccnz .LBB0_140
	v_mul_f32_e32 v151, 0xbfb8aa3b, v96
	v_exp_f32_e32 v151, v151
	v_mul_f32_e32 v148, 0xbfb8aa3b, v94
	v_mul_f32_e32 v149, 0xbfb8aa3b, v95
	v_exp_f32_e32 v148, v148
	v_add_f32_e32 v151, 1.0, v151
	v_rcp_f32_e32 v152, v151
	v_mul_f32_e32 v151, 0xbfb8aa3b, v97
	v_exp_f32_e32 v151, v151
	v_exp_f32_e32 v149, v149
	v_add_f32_e32 v148, 1.0, v148
	v_rcp_f32_e32 v148, v148
	v_add_f32_e32 v151, 1.0, v151
	v_rcp_f32_e32 v153, v151
	v_mul_f32_e32 v151, 0xbfb8aa3b, v92
	v_add_f32_e32 v149, 1.0, v149
	v_exp_f32_e32 v151, v151
	v_rcp_f32_e32 v149, v149
	v_pk_mul_f32 v[96:97], v[96:97], v[152:153]
	v_add_f32_e32 v151, 1.0, v151
	v_pk_mul_f32 v[94:95], v[94:95], v[148:149]
	v_mul_f32_e32 v148, 0xbfb8aa3b, v90
	v_mul_f32_e32 v149, 0xbfb8aa3b, v91
	v_rcp_f32_e32 v152, v151
	v_mul_f32_e32 v151, 0xbfb8aa3b, v93
	v_exp_f32_e32 v148, v148
	v_exp_f32_e32 v149, v149
	v_exp_f32_e32 v151, v151
	v_add_f32_e32 v148, 1.0, v148
	v_add_f32_e32 v149, 1.0, v149
	v_add_f32_e32 v151, 1.0, v151
	v_rcp_f32_e32 v148, v148
	v_rcp_f32_e32 v149, v149
	v_rcp_f32_e32 v153, v151
	v_pk_mul_f32 v[90:91], v[90:91], v[148:149]
	v_pk_mul_f32 v[92:93], v[92:93], v[152:153]
.LBB0_140:
	v_or_b32_e32 v148, 32, v142
	v_ashrrev_i32_e32 v149, 31, v148
	v_lshl_add_u32 v175, v148, 8, v174
	v_cvt_pk_bf16_f32 v154, v94, v95
	v_cvt_pk_bf16_f32 v155, v96, v97
	v_mov_b32_e32 v151, v150
	v_cvt_pk_bf16_f32 v156, v90, v91
	v_cvt_pk_bf16_f32 v157, v92, v93
	buffer_store_dwordx4 v[154:157], v175, s[84:87], 0 offen
	v_pk_mul_f32 v[86:87], v[86:87], v[150:151]
	s_and_b64 vcc, exec, s[4:5]
	v_mov_b32_e32 v154, v150
	v_mov_b32_e32 v155, v150
	v_pk_mul_f32 v[88:89], v[88:89], v[154:155]
	v_pk_mul_f32 v[84:85], v[84:85], v[154:155]
	v_pk_mul_f32 v[82:83], v[82:83], v[150:151]
	s_cbranch_vccnz .LBB0_142
	v_mul_f32_e32 v150, 0xbfb8aa3b, v86
	v_mul_f32_e32 v151, 0xbfb8aa3b, v87
	v_mul_f32_e32 v154, 0xbfb8aa3b, v88
	v_mul_f32_e32 v155, 0xbfb8aa3b, v89
	v_exp_f32_e32 v150, v150
	v_exp_f32_e32 v151, v151
	v_exp_f32_e32 v154, v154
	v_exp_f32_e32 v155, v155
	v_add_f32_e32 v150, 1.0, v150
	v_add_f32_e32 v151, 1.0, v151
	v_add_f32_e32 v154, 1.0, v154
	v_add_f32_e32 v155, 1.0, v155
	v_rcp_f32_e32 v150, v150
	v_rcp_f32_e32 v151, v151
	v_rcp_f32_e32 v154, v154
	v_rcp_f32_e32 v155, v155
	v_pk_mul_f32 v[86:87], v[86:87], v[150:151]
	v_mul_f32_e32 v150, 0xbfb8aa3b, v82
	v_pk_mul_f32 v[88:89], v[88:89], v[154:155]
	v_mul_f32_e32 v151, 0xbfb8aa3b, v83
	v_mul_f32_e32 v154, 0xbfb8aa3b, v84
	v_mul_f32_e32 v155, 0xbfb8aa3b, v85
	v_exp_f32_e32 v150, v150
	v_exp_f32_e32 v151, v151
	v_exp_f32_e32 v154, v154
	v_exp_f32_e32 v155, v155
	v_add_f32_e32 v150, 1.0, v150
	v_add_f32_e32 v151, 1.0, v151
	v_add_f32_e32 v154, 1.0, v154
	v_add_f32_e32 v155, 1.0, v155
	v_rcp_f32_e32 v150, v150
	v_rcp_f32_e32 v151, v151
	v_rcp_f32_e32 v154, v154
	v_rcp_f32_e32 v155, v155
	v_pk_mul_f32 v[82:83], v[82:83], v[150:151]
	v_pk_mul_f32 v[84:85], v[84:85], v[154:155]
.LBB0_142:
	v_cvt_pk_bf16_f32 v154, v86, v87
	v_cvt_pk_bf16_f32 v155, v88, v89
	v_cvt_pk_bf16_f32 v156, v82, v83
	s_nop 0
	v_cvt_pk_bf16_f32 v157, v84, v85
	ds_read_b32 v152, v168 offset:192
	s_nop 0
	s_and_b64 vcc, exec, s[4:5]
	buffer_store_dwordx4 v[154:157], v175, s[84:87], s88 offen
	s_waitcnt lgkmcnt(0)
	v_pk_mul_f32 v[80:81], v[80:81], v[152:153] op_sel_hi:[1,0]
	v_pk_mul_f32 v[78:79], v[78:79], v[152:153] op_sel_hi:[1,0]
	v_pk_mul_f32 v[76:77], v[76:77], v[152:153] op_sel_hi:[1,0]
	v_pk_mul_f32 v[74:75], v[74:75], v[152:153] op_sel_hi:[1,0]
	s_cbranch_vccnz .LBB0_144
	v_mul_f32_e32 v153, 0xbfb8aa3b, v80
	v_exp_f32_e32 v153, v153
	v_mul_f32_e32 v150, 0xbfb8aa3b, v78
	v_mul_f32_e32 v151, 0xbfb8aa3b, v79
	v_exp_f32_e32 v150, v150
	v_add_f32_e32 v153, 1.0, v153
	v_rcp_f32_e32 v154, v153
	v_mul_f32_e32 v153, 0xbfb8aa3b, v81
	v_exp_f32_e32 v153, v153
	v_exp_f32_e32 v151, v151
	v_add_f32_e32 v150, 1.0, v150
	v_rcp_f32_e32 v150, v150
	v_add_f32_e32 v153, 1.0, v153
	v_rcp_f32_e32 v155, v153
	v_mul_f32_e32 v153, 0xbfb8aa3b, v76
	v_add_f32_e32 v151, 1.0, v151
	v_exp_f32_e32 v153, v153
	v_rcp_f32_e32 v151, v151
	v_pk_mul_f32 v[80:81], v[80:81], v[154:155]
	v_add_f32_e32 v153, 1.0, v153
	v_pk_mul_f32 v[78:79], v[78:79], v[150:151]
	v_mul_f32_e32 v150, 0xbfb8aa3b, v74
	v_mul_f32_e32 v151, 0xbfb8aa3b, v75
	v_rcp_f32_e32 v154, v153
	v_mul_f32_e32 v153, 0xbfb8aa3b, v77
	v_exp_f32_e32 v150, v150
	v_exp_f32_e32 v151, v151
	v_exp_f32_e32 v153, v153
	v_add_f32_e32 v150, 1.0, v150
	v_add_f32_e32 v151, 1.0, v151
	v_add_f32_e32 v153, 1.0, v153
	v_rcp_f32_e32 v150, v150
	v_rcp_f32_e32 v151, v151
	v_rcp_f32_e32 v155, v153
	v_pk_mul_f32 v[74:75], v[74:75], v[150:151]
	v_pk_mul_f32 v[76:77], v[76:77], v[154:155]
.LBB0_144:
	v_or_b32_e32 v150, 48, v142
	v_ashrrev_i32_e32 v151, 31, v150
	v_lshl_add_u32 v175, v150, 8, v174
	v_cvt_pk_bf16_f32 v156, v78, v79
	v_cvt_pk_bf16_f32 v157, v80, v81
	v_mov_b32_e32 v153, v152
	v_cvt_pk_bf16_f32 v158, v74, v75
	v_cvt_pk_bf16_f32 v159, v76, v77
	buffer_store_dwordx4 v[156:159], v175, s[84:87], 0 offen
	v_pk_mul_f32 v[70:71], v[70:71], v[152:153]
	s_and_b64 vcc, exec, s[4:5]
	v_mov_b32_e32 v156, v152
	v_mov_b32_e32 v157, v152
	v_pk_mul_f32 v[72:73], v[72:73], v[156:157]
	v_pk_mul_f32 v[68:69], v[68:69], v[156:157]
	v_pk_mul_f32 v[66:67], v[66:67], v[152:153]
	s_cbranch_vccnz .LBB0_146
	v_mul_f32_e32 v152, 0xbfb8aa3b, v70
	v_mul_f32_e32 v153, 0xbfb8aa3b, v71
	v_mul_f32_e32 v156, 0xbfb8aa3b, v72
	v_mul_f32_e32 v157, 0xbfb8aa3b, v73
	v_exp_f32_e32 v152, v152
	v_exp_f32_e32 v153, v153
	v_exp_f32_e32 v156, v156
	v_exp_f32_e32 v157, v157
	v_add_f32_e32 v152, 1.0, v152
	v_add_f32_e32 v153, 1.0, v153
	v_add_f32_e32 v156, 1.0, v156
	v_add_f32_e32 v157, 1.0, v157
	v_rcp_f32_e32 v152, v152
	v_rcp_f32_e32 v153, v153
	v_rcp_f32_e32 v156, v156
	v_rcp_f32_e32 v157, v157
	v_pk_mul_f32 v[70:71], v[70:71], v[152:153]
	v_mul_f32_e32 v152, 0xbfb8aa3b, v66
	v_pk_mul_f32 v[72:73], v[72:73], v[156:157]
	v_mul_f32_e32 v153, 0xbfb8aa3b, v67
	v_mul_f32_e32 v156, 0xbfb8aa3b, v68
	v_mul_f32_e32 v157, 0xbfb8aa3b, v69
	v_exp_f32_e32 v152, v152
	v_exp_f32_e32 v153, v153
	v_exp_f32_e32 v156, v156
	v_exp_f32_e32 v157, v157
	v_add_f32_e32 v152, 1.0, v152
	v_add_f32_e32 v153, 1.0, v153
	v_add_f32_e32 v156, 1.0, v156
	v_add_f32_e32 v157, 1.0, v157
	v_rcp_f32_e32 v152, v152
	v_rcp_f32_e32 v153, v153
	v_rcp_f32_e32 v156, v156
	v_rcp_f32_e32 v157, v157
	v_pk_mul_f32 v[66:67], v[66:67], v[152:153]
	v_pk_mul_f32 v[68:69], v[68:69], v[156:157]
.LBB0_146:
	v_cvt_pk_bf16_f32 v156, v70, v71
	v_cvt_pk_bf16_f32 v157, v72, v73
	v_cvt_pk_bf16_f32 v158, v66, v67
	s_nop 0
	v_cvt_pk_bf16_f32 v159, v68, v69
	ds_read_b32 v154, v168 offset:512
	s_nop 0
	s_and_b64 vcc, exec, s[4:5]
	buffer_store_dwordx4 v[156:159], v175, s[84:87], s88 offen
	s_waitcnt lgkmcnt(0)
	v_pk_mul_f32 v[64:65], v[64:65], v[154:155] op_sel_hi:[1,0]
	v_pk_mul_f32 v[62:63], v[62:63], v[154:155] op_sel_hi:[1,0]
	v_pk_mul_f32 v[60:61], v[60:61], v[154:155] op_sel_hi:[1,0]
	v_pk_mul_f32 v[58:59], v[58:59], v[154:155] op_sel_hi:[1,0]
	s_cbranch_vccnz .LBB0_148
	v_mul_f32_e32 v155, 0xbfb8aa3b, v64
	v_exp_f32_e32 v155, v155
	v_mul_f32_e32 v152, 0xbfb8aa3b, v62
	v_mul_f32_e32 v153, 0xbfb8aa3b, v63
	v_exp_f32_e32 v152, v152
	v_add_f32_e32 v155, 1.0, v155
	v_rcp_f32_e32 v156, v155
	v_mul_f32_e32 v155, 0xbfb8aa3b, v65
	v_exp_f32_e32 v155, v155
	v_exp_f32_e32 v153, v153
	v_add_f32_e32 v152, 1.0, v152
	v_rcp_f32_e32 v152, v152
	v_add_f32_e32 v155, 1.0, v155
	v_rcp_f32_e32 v157, v155
	v_mul_f32_e32 v155, 0xbfb8aa3b, v60
	v_add_f32_e32 v153, 1.0, v153
	v_exp_f32_e32 v155, v155
	v_rcp_f32_e32 v153, v153
	v_pk_mul_f32 v[64:65], v[64:65], v[156:157]
	v_add_f32_e32 v155, 1.0, v155
	v_pk_mul_f32 v[62:63], v[62:63], v[152:153]
	v_mul_f32_e32 v152, 0xbfb8aa3b, v58
	v_mul_f32_e32 v153, 0xbfb8aa3b, v59
	v_rcp_f32_e32 v156, v155
	v_mul_f32_e32 v155, 0xbfb8aa3b, v61
	v_exp_f32_e32 v152, v152
	v_exp_f32_e32 v153, v153
	v_exp_f32_e32 v155, v155
	v_add_f32_e32 v152, 1.0, v152
	v_add_f32_e32 v153, 1.0, v153
	v_add_f32_e32 v155, 1.0, v155
	v_rcp_f32_e32 v152, v152
	v_rcp_f32_e32 v153, v153
	v_rcp_f32_e32 v157, v155
	v_pk_mul_f32 v[58:59], v[58:59], v[152:153]
	v_pk_mul_f32 v[60:61], v[60:61], v[156:157]
.LBB0_148:
	v_add_u32_e32 v152, 0x80, v142
	v_ashrrev_i32_e32 v153, 31, v152
	v_lshl_add_u32 v175, v152, 8, v174
	v_cvt_pk_bf16_f32 v158, v62, v63
	v_cvt_pk_bf16_f32 v159, v64, v65
	v_mov_b32_e32 v155, v154
	v_cvt_pk_bf16_f32 v160, v58, v59
	v_cvt_pk_bf16_f32 v161, v60, v61
	buffer_store_dwordx4 v[158:161], v175, s[84:87], 0 offen
	v_pk_mul_f32 v[54:55], v[54:55], v[154:155]
	s_and_b64 vcc, exec, s[4:5]
	v_mov_b32_e32 v158, v154
	v_mov_b32_e32 v159, v154
	v_pk_mul_f32 v[56:57], v[56:57], v[158:159]
	v_pk_mul_f32 v[52:53], v[52:53], v[158:159]
	v_pk_mul_f32 v[50:51], v[50:51], v[154:155]
	s_cbranch_vccnz .LBB0_150
	v_mul_f32_e32 v154, 0xbfb8aa3b, v54
	v_mul_f32_e32 v155, 0xbfb8aa3b, v55
	v_mul_f32_e32 v158, 0xbfb8aa3b, v56
	v_mul_f32_e32 v159, 0xbfb8aa3b, v57
	v_exp_f32_e32 v154, v154
	v_exp_f32_e32 v155, v155
	v_exp_f32_e32 v158, v158
	v_exp_f32_e32 v159, v159
	v_add_f32_e32 v154, 1.0, v154
	v_add_f32_e32 v155, 1.0, v155
	v_add_f32_e32 v158, 1.0, v158
	v_add_f32_e32 v159, 1.0, v159
	v_rcp_f32_e32 v154, v154
	v_rcp_f32_e32 v155, v155
	v_rcp_f32_e32 v158, v158
	v_rcp_f32_e32 v159, v159
	v_pk_mul_f32 v[54:55], v[54:55], v[154:155]
	v_mul_f32_e32 v154, 0xbfb8aa3b, v50
	v_pk_mul_f32 v[56:57], v[56:57], v[158:159]
	v_mul_f32_e32 v155, 0xbfb8aa3b, v51
	v_mul_f32_e32 v158, 0xbfb8aa3b, v52
	v_mul_f32_e32 v159, 0xbfb8aa3b, v53
	v_exp_f32_e32 v154, v154
	v_exp_f32_e32 v155, v155
	v_exp_f32_e32 v158, v158
	v_exp_f32_e32 v159, v159
	v_add_f32_e32 v154, 1.0, v154
	v_add_f32_e32 v155, 1.0, v155
	v_add_f32_e32 v158, 1.0, v158
	v_add_f32_e32 v159, 1.0, v159
	v_rcp_f32_e32 v154, v154
	v_rcp_f32_e32 v155, v155
	v_rcp_f32_e32 v158, v158
	v_rcp_f32_e32 v159, v159
	v_pk_mul_f32 v[50:51], v[50:51], v[154:155]
	v_pk_mul_f32 v[52:53], v[52:53], v[158:159]
.LBB0_150:
	v_cvt_pk_bf16_f32 v158, v54, v55
	v_cvt_pk_bf16_f32 v159, v56, v57
	v_cvt_pk_bf16_f32 v160, v50, v51
	s_nop 0
	v_cvt_pk_bf16_f32 v161, v52, v53
	ds_read_b32 v156, v168 offset:576
	s_nop 0
	s_and_b64 vcc, exec, s[4:5]
	buffer_store_dwordx4 v[158:161], v175, s[84:87], s88 offen
	s_waitcnt lgkmcnt(0)
	v_pk_mul_f32 v[48:49], v[48:49], v[156:157] op_sel_hi:[1,0]
	v_pk_mul_f32 v[46:47], v[46:47], v[156:157] op_sel_hi:[1,0]
	v_pk_mul_f32 v[44:45], v[44:45], v[156:157] op_sel_hi:[1,0]
	v_pk_mul_f32 v[42:43], v[42:43], v[156:157] op_sel_hi:[1,0]
	s_cbranch_vccnz .LBB0_152
	v_mul_f32_e32 v157, 0xbfb8aa3b, v48
	v_exp_f32_e32 v157, v157
	v_mul_f32_e32 v154, 0xbfb8aa3b, v46
	v_mul_f32_e32 v155, 0xbfb8aa3b, v47
	v_exp_f32_e32 v154, v154
	v_add_f32_e32 v157, 1.0, v157
	v_rcp_f32_e32 v158, v157
	v_mul_f32_e32 v157, 0xbfb8aa3b, v49
	v_exp_f32_e32 v157, v157
	v_exp_f32_e32 v155, v155
	v_add_f32_e32 v154, 1.0, v154
	v_rcp_f32_e32 v154, v154
	v_add_f32_e32 v157, 1.0, v157
	v_rcp_f32_e32 v159, v157
	v_mul_f32_e32 v157, 0xbfb8aa3b, v44
	v_add_f32_e32 v155, 1.0, v155
	v_exp_f32_e32 v157, v157
	v_rcp_f32_e32 v155, v155
	v_pk_mul_f32 v[48:49], v[48:49], v[158:159]
	v_add_f32_e32 v157, 1.0, v157
	v_pk_mul_f32 v[46:47], v[46:47], v[154:155]
	v_mul_f32_e32 v154, 0xbfb8aa3b, v42
	v_mul_f32_e32 v155, 0xbfb8aa3b, v43
	v_rcp_f32_e32 v158, v157
	v_mul_f32_e32 v157, 0xbfb8aa3b, v45
	v_exp_f32_e32 v154, v154
	v_exp_f32_e32 v155, v155
	v_exp_f32_e32 v157, v157
	v_add_f32_e32 v154, 1.0, v154
	v_add_f32_e32 v155, 1.0, v155
	v_add_f32_e32 v157, 1.0, v157
	v_rcp_f32_e32 v154, v154
	v_rcp_f32_e32 v155, v155
	v_rcp_f32_e32 v159, v157
	v_pk_mul_f32 v[42:43], v[42:43], v[154:155]
	v_pk_mul_f32 v[44:45], v[44:45], v[158:159]
.LBB0_152:
	v_add_u32_e32 v154, 0x90, v142
	v_ashrrev_i32_e32 v155, 31, v154
	v_mov_b32_e32 v157, v156
	v_lshl_add_u32 v175, v154, 8, v174
	v_mov_b32_e32 v160, v156
	v_mov_b32_e32 v161, v156
	v_pk_mul_f32 v[40:41], v[40:41], v[160:161]
	v_pk_mul_f32 v[38:39], v[38:39], v[156:157]
	v_pk_mul_f32 v[36:37], v[36:37], v[160:161]
	s_and_b64 vcc, exec, s[4:5]
	v_pk_mul_f32 v[34:35], v[34:35], v[156:157]
	v_cvt_pk_bf16_f32 v170, v46, v47
	v_cvt_pk_bf16_f32 v171, v48, v49
	v_cvt_pk_bf16_f32 v172, v42, v43
	v_cvt_pk_bf16_f32 v173, v44, v45
	buffer_store_dwordx4 v[170:173], v175, s[84:87], 0 offen
	s_cbranch_vccnz .LBB0_154
	v_mul_f32_e32 v156, 0xbfb8aa3b, v38
	v_mul_f32_e32 v157, 0xbfb8aa3b, v39
	v_mul_f32_e32 v160, 0xbfb8aa3b, v40
	v_mul_f32_e32 v161, 0xbfb8aa3b, v41
	v_exp_f32_e32 v156, v156
	v_exp_f32_e32 v157, v157
	v_exp_f32_e32 v160, v160
	v_exp_f32_e32 v161, v161
	v_add_f32_e32 v156, 1.0, v156
	v_add_f32_e32 v157, 1.0, v157
	v_add_f32_e32 v160, 1.0, v160
	v_add_f32_e32 v161, 1.0, v161
	v_rcp_f32_e32 v156, v156
	v_rcp_f32_e32 v157, v157
	v_rcp_f32_e32 v160, v160
	v_rcp_f32_e32 v161, v161
	v_pk_mul_f32 v[38:39], v[38:39], v[156:157]
	v_mul_f32_e32 v156, 0xbfb8aa3b, v34
	v_pk_mul_f32 v[40:41], v[40:41], v[160:161]
	v_mul_f32_e32 v157, 0xbfb8aa3b, v35
	v_mul_f32_e32 v160, 0xbfb8aa3b, v36
	v_mul_f32_e32 v161, 0xbfb8aa3b, v37
	v_exp_f32_e32 v156, v156
	v_exp_f32_e32 v157, v157
	v_exp_f32_e32 v160, v160
	v_exp_f32_e32 v161, v161
	v_add_f32_e32 v156, 1.0, v156
	v_add_f32_e32 v157, 1.0, v157
	v_add_f32_e32 v160, 1.0, v160
	v_add_f32_e32 v161, 1.0, v161
	v_rcp_f32_e32 v156, v156
	v_rcp_f32_e32 v157, v157
	v_rcp_f32_e32 v160, v160
	v_rcp_f32_e32 v161, v161
	v_pk_mul_f32 v[34:35], v[34:35], v[156:157]
	v_pk_mul_f32 v[36:37], v[36:37], v[160:161]
.LBB0_154:
	s_nop 0
	v_cvt_pk_bf16_f32 v170, v38, v39
	v_cvt_pk_bf16_f32 v171, v40, v41
	v_cvt_pk_bf16_f32 v172, v34, v35
	v_cvt_pk_bf16_f32 v173, v36, v37
	ds_read_b32 v158, v168 offset:640
	s_nop 0
	s_and_b64 vcc, exec, s[4:5]
	buffer_store_dwordx4 v[170:173], v175, s[84:87], s88 offen
	s_waitcnt lgkmcnt(0)
	v_pk_mul_f32 v[32:33], v[32:33], v[158:159] op_sel_hi:[1,0]
	v_pk_mul_f32 v[30:31], v[30:31], v[158:159] op_sel_hi:[1,0]
	v_pk_mul_f32 v[28:29], v[28:29], v[158:159] op_sel_hi:[1,0]
	v_pk_mul_f32 v[26:27], v[26:27], v[158:159] op_sel_hi:[1,0]
	s_cbranch_vccnz .LBB0_156
	v_mul_f32_e32 v159, 0xbfb8aa3b, v32
	v_exp_f32_e32 v159, v159
	v_mul_f32_e32 v156, 0xbfb8aa3b, v30
	v_mul_f32_e32 v157, 0xbfb8aa3b, v31
	v_exp_f32_e32 v156, v156
	v_add_f32_e32 v159, 1.0, v159
	v_rcp_f32_e32 v160, v159
	v_mul_f32_e32 v159, 0xbfb8aa3b, v33
	v_exp_f32_e32 v159, v159
	v_exp_f32_e32 v157, v157
	v_add_f32_e32 v156, 1.0, v156
	v_rcp_f32_e32 v156, v156
	v_add_f32_e32 v159, 1.0, v159
	v_rcp_f32_e32 v161, v159
	v_mul_f32_e32 v159, 0xbfb8aa3b, v28
	v_add_f32_e32 v157, 1.0, v157
	v_exp_f32_e32 v159, v159
	v_rcp_f32_e32 v157, v157
	v_pk_mul_f32 v[32:33], v[32:33], v[160:161]
	v_add_f32_e32 v159, 1.0, v159
	v_pk_mul_f32 v[30:31], v[30:31], v[156:157]
	v_mul_f32_e32 v156, 0xbfb8aa3b, v26
	v_mul_f32_e32 v157, 0xbfb8aa3b, v27
	v_rcp_f32_e32 v160, v159
	v_mul_f32_e32 v159, 0xbfb8aa3b, v29
	v_exp_f32_e32 v156, v156
	v_exp_f32_e32 v157, v157
	v_exp_f32_e32 v159, v159
	v_add_f32_e32 v156, 1.0, v156
	v_add_f32_e32 v157, 1.0, v157
	v_add_f32_e32 v159, 1.0, v159
	v_rcp_f32_e32 v156, v156
	v_rcp_f32_e32 v157, v157
	v_rcp_f32_e32 v161, v159
	v_pk_mul_f32 v[26:27], v[26:27], v[156:157]
	v_pk_mul_f32 v[28:29], v[28:29], v[160:161]
.LBB0_156:
	v_add_u32_e32 v156, 0xa0, v142
	v_ashrrev_i32_e32 v157, 31, v156
	v_lshl_add_u32 v175, v156, 8, v174
	v_cvt_pk_bf16_f32 v170, v30, v31
	v_cvt_pk_bf16_f32 v171, v32, v33
	v_mov_b32_e32 v159, v158
	v_cvt_pk_bf16_f32 v172, v26, v27
	v_cvt_pk_bf16_f32 v173, v28, v29
	buffer_store_dwordx4 v[170:173], v175, s[84:87], 0 offen
	v_pk_mul_f32 v[22:23], v[22:23], v[158:159]
	s_and_b64 vcc, exec, s[4:5]
	v_mov_b32_e32 v170, v158
	v_mov_b32_e32 v171, v158
	v_pk_mul_f32 v[24:25], v[24:25], v[170:171]
	v_pk_mul_f32 v[20:21], v[20:21], v[170:171]
	v_pk_mul_f32 v[18:19], v[18:19], v[158:159]
	s_cbranch_vccnz .LBB0_158
	v_mul_f32_e32 v169, 0xbfb8aa3b, v24
	v_exp_f32_e32 v169, v169
	v_mul_f32_e32 v158, 0xbfb8aa3b, v22
	v_mul_f32_e32 v159, 0xbfb8aa3b, v23
	v_exp_f32_e32 v158, v158
	v_add_f32_e32 v169, 1.0, v169
	v_rcp_f32_e32 v170, v169
	v_mul_f32_e32 v169, 0xbfb8aa3b, v25
	v_exp_f32_e32 v169, v169
	v_exp_f32_e32 v159, v159
	v_add_f32_e32 v158, 1.0, v158
	v_rcp_f32_e32 v158, v158
	v_add_f32_e32 v169, 1.0, v169
	v_rcp_f32_e32 v171, v169
	v_mul_f32_e32 v169, 0xbfb8aa3b, v20
	v_add_f32_e32 v159, 1.0, v159
	v_exp_f32_e32 v169, v169
	v_rcp_f32_e32 v159, v159
	v_pk_mul_f32 v[24:25], v[24:25], v[170:171]
	v_add_f32_e32 v169, 1.0, v169
	v_pk_mul_f32 v[22:23], v[22:23], v[158:159]
	v_mul_f32_e32 v158, 0xbfb8aa3b, v18
	v_mul_f32_e32 v159, 0xbfb8aa3b, v19
	v_rcp_f32_e32 v170, v169
	v_mul_f32_e32 v169, 0xbfb8aa3b, v21
	v_exp_f32_e32 v158, v158
	v_exp_f32_e32 v159, v159
	v_exp_f32_e32 v169, v169
	v_add_f32_e32 v158, 1.0, v158
	v_add_f32_e32 v159, 1.0, v159
	v_add_f32_e32 v169, 1.0, v169
	v_rcp_f32_e32 v158, v158
	v_rcp_f32_e32 v159, v159
	v_rcp_f32_e32 v171, v169
	v_pk_mul_f32 v[18:19], v[18:19], v[158:159]
	v_pk_mul_f32 v[20:21], v[20:21], v[170:171]
.LBB0_158:
	v_cvt_pk_bf16_f32 v170, v22, v23
	v_cvt_pk_bf16_f32 v171, v24, v25
	v_cvt_pk_bf16_f32 v172, v18, v19
	s_nop 0
	v_cvt_pk_bf16_f32 v173, v20, v21
	ds_read_b32 v160, v168 offset:704
	s_nop 0
	s_and_b64 vcc, exec, s[4:5]
	buffer_store_dwordx4 v[170:173], v175, s[84:87], s88 offen
	s_waitcnt lgkmcnt(0)
	v_pk_mul_f32 v[16:17], v[16:17], v[160:161] op_sel_hi:[1,0]
	v_pk_mul_f32 v[14:15], v[14:15], v[160:161] op_sel_hi:[1,0]
	v_pk_mul_f32 v[12:13], v[12:13], v[160:161] op_sel_hi:[1,0]
	v_pk_mul_f32 v[10:11], v[10:11], v[160:161] op_sel_hi:[1,0]
	s_cbranch_vccnz .LBB0_160
	v_mul_f32_e32 v161, 0xbfb8aa3b, v16
	v_exp_f32_e32 v161, v161
	v_mul_f32_e32 v158, 0xbfb8aa3b, v14
	v_mul_f32_e32 v159, 0xbfb8aa3b, v15
	v_exp_f32_e32 v158, v158
	v_add_f32_e32 v161, 1.0, v161
	v_rcp_f32_e32 v168, v161
	v_mul_f32_e32 v161, 0xbfb8aa3b, v17
	v_exp_f32_e32 v161, v161
	v_exp_f32_e32 v159, v159
	v_add_f32_e32 v158, 1.0, v158
	v_rcp_f32_e32 v158, v158
	v_add_f32_e32 v161, 1.0, v161
	v_rcp_f32_e32 v169, v161
	v_mul_f32_e32 v161, 0xbfb8aa3b, v12
	v_add_f32_e32 v159, 1.0, v159
	v_exp_f32_e32 v161, v161
	v_rcp_f32_e32 v159, v159
	v_pk_mul_f32 v[16:17], v[16:17], v[168:169]
	v_add_f32_e32 v161, 1.0, v161
	v_pk_mul_f32 v[14:15], v[14:15], v[158:159]
	v_mul_f32_e32 v158, 0xbfb8aa3b, v10
	v_mul_f32_e32 v159, 0xbfb8aa3b, v11
	v_rcp_f32_e32 v168, v161
	v_mul_f32_e32 v161, 0xbfb8aa3b, v13
	v_exp_f32_e32 v158, v158
	v_exp_f32_e32 v159, v159
	v_exp_f32_e32 v161, v161
	v_add_f32_e32 v158, 1.0, v158
	v_add_f32_e32 v159, 1.0, v159
	v_add_f32_e32 v161, 1.0, v161
	v_rcp_f32_e32 v158, v158
	v_rcp_f32_e32 v159, v159
	v_rcp_f32_e32 v169, v161
	v_pk_mul_f32 v[10:11], v[10:11], v[158:159]
	v_pk_mul_f32 v[12:13], v[12:13], v[168:169]
.LBB0_160:
	v_add_u32_e32 v158, 0xb0, v142
	v_ashrrev_i32_e32 v159, 31, v158
	v_lshl_add_u32 v175, v158, 8, v174
	v_cvt_pk_bf16_f32 v168, v14, v15
	v_cvt_pk_bf16_f32 v169, v16, v17
	v_mov_b32_e32 v161, v160
	v_cvt_pk_bf16_f32 v170, v10, v11
	v_cvt_pk_bf16_f32 v171, v12, v13
	buffer_store_dwordx4 v[168:171], v175, s[84:87], 0 offen
	v_pk_mul_f32 v[6:7], v[6:7], v[160:161]
	s_and_b64 vcc, exec, s[4:5]
	v_mov_b32_e32 v168, v160
	v_mov_b32_e32 v169, v160
	v_pk_mul_f32 v[8:9], v[8:9], v[168:169]
	v_pk_mul_f32 v[4:5], v[4:5], v[168:169]
	v_pk_mul_f32 v[2:3], v[2:3], v[160:161]
	s_cbranch_vccnz .LBB0_162
	v_mul_f32_e32 v160, 0xbfb8aa3b, v6
	v_mul_f32_e32 v161, 0xbfb8aa3b, v7
	v_mul_f32_e32 v168, 0xbfb8aa3b, v8
	v_mul_f32_e32 v169, 0xbfb8aa3b, v9
	v_mul_f32_e32 v170, 0xbfb8aa3b, v2
	v_mul_f32_e32 v171, 0xbfb8aa3b, v3
	v_mul_f32_e32 v172, 0xbfb8aa3b, v4
	v_mul_f32_e32 v173, 0xbfb8aa3b, v5
	v_exp_f32_e32 v160, v160
	v_exp_f32_e32 v161, v161
	v_exp_f32_e32 v168, v168
	v_exp_f32_e32 v169, v169
	v_exp_f32_e32 v170, v170
	v_exp_f32_e32 v171, v171
	v_exp_f32_e32 v172, v172
	v_exp_f32_e32 v173, v173
	v_add_f32_e32 v160, 1.0, v160
	v_add_f32_e32 v161, 1.0, v161
	v_add_f32_e32 v168, 1.0, v168
	v_add_f32_e32 v169, 1.0, v169
	v_add_f32_e32 v170, 1.0, v170
	v_add_f32_e32 v171, 1.0, v171
	v_add_f32_e32 v172, 1.0, v172
	v_add_f32_e32 v173, 1.0, v173
	v_rcp_f32_e32 v160, v160
	v_rcp_f32_e32 v161, v161
	v_rcp_f32_e32 v168, v168
	v_rcp_f32_e32 v169, v169
	v_rcp_f32_e32 v170, v170
	v_rcp_f32_e32 v172, v172
	v_rcp_f32_e32 v173, v173
	v_rcp_f32_e32 v171, v171
	v_pk_mul_f32 v[8:9], v[8:9], v[168:169]
	v_pk_mul_f32 v[6:7], v[6:7], v[160:161]
	v_pk_mul_f32 v[4:5], v[4:5], v[172:173]
	v_pk_mul_f32 v[2:3], v[2:3], v[170:171]
.LBB0_162:
	s_and_b32 s0, s43, -8
	s_cmp_lg_u32 s0, 16
	s_nop 0
	v_cvt_pk_bf16_f32 v168, v6, v7
	v_cvt_pk_bf16_f32 v169, v8, v9
	v_cvt_pk_bf16_f32 v170, v2, v3
	v_cvt_pk_bf16_f32 v171, v4, v5
	buffer_store_dwordx4 v[168:171], v175, s[84:87], s88 offen
	s_cbranch_scc0 .LBB0_164
	s_cmp_eq_u32 s42, 3
	s_mov_b64 s[0:1], -1
	s_cbranch_scc1 .LBB0_125
	s_branch .LBB0_197
